# attention QK^T: 6-deep K-fragment register ring with counted lgkmcnt (was single fragment + lgkmcnt(0) per MFMA); VGPR alloc 248->256
# speedup vs baseline: 1.0068x; 1.0068x over previous
; DI void partialSM(f32x16& p0, f32x16& p1, float& m_reg, float& mn, float& alpha) {
;   constexpr float C = ATT_SCALE * 1.4426950408889634f;
;   float pmax = p0[0];
; #pragma unroll
;   for (int r = 1; r < 16; ++r) pmax = fmaxf(pmax, p0[r]);
; #pragma unroll
;   for (int r = 0; r < 16; ++r) pmax = fmaxf(pmax, p1[r]);
;   { auto rr = __builtin_amdgcn_permlane32_swap(__float_as_uint(pmax), __float_as_uint(pmax), false, false);
;     pmax = fmaxf(__uint_as_float(rr[0]), __uint_as_float(rr[1])); }
;   if (__builtin_expect(__all(pmax - m_reg <= ATT_THR / ATT_SCALE), 1)) { mn = m_reg; alpha = 1.f; }
;   else { mn = fmaxf(m_reg, pmax); alpha = __builtin_amdgcn_exp2f((m_reg - mn) * C); m_reg = mn; }
; DI void qkt(f32x16& p0, f32x16& p1, const char* Ks, const bf16x8* qr, int r32, int hi) {
;   p0 = f32x16{}; p1 = f32x16{};
; #pragma unroll
;   for (int d0 = 0; d0 < 12; ++d0) { int cb = (d0 * 16 + hi * 8) * 2;
;     bf16x8 b0 = *reinterpret_cast<const bf16x8*>(Ks + KSWZ(r32, cb));
;     bf16x8 b1 = *reinterpret_cast<const bf16x8*>(Ks + KSWZ(32 + r32, cb));
;     p0 = __builtin_amdgcn_mfma_f32_32x32x16_bf16(b0, qr[d0], p0, 0, 0, 0);
;     p1 = __builtin_amdgcn_mfma_f32_32x32x16_bf16(b1, qr[d0], p1, 0, 0, 0); }
; }
.LBB0_828:
	s_and_b32 s83, s82, 1
	s_mul_i32 s10, s83, 0x6400
	s_add_i32 s10, s10, 16
	v_add3_u32 v228, s10, v96, v210
	ds_read_b128 v[212:215], v228 offset:32768
	ds_read_b128 v[216:219], v228 offset:32800
	ds_read_b128 v[220:223], v228 offset:45568
	ds_read_b128 v[224:227], v228 offset:45600
	ds_read_b128 v[244:247], v228 offset:32832
	ds_read_b128 v[248:251], v228 offset:45632
	v_ashrrev_i32_e32 v177, 31, v176
	v_lshl_add_u64 v[64:65], s[16:17], 0, v[178:179]
	v_lshlrev_b64 v[66:67], 11, v[176:177]
	v_lshl_add_u64 v[66:67], v[168:169], 0, v[66:67]
	global_load_dwordx4 v[162:165], v[64:65], off
	global_load_dwordx4 v[158:161], v[66:67], off
	v_lshl_add_u64 v[64:65], s[16:17], 0, v[174:175]
	v_lshl_add_u64 v[66:67], s[16:17], 0, v[172:173]
	global_load_dwordx4 v[154:157], v[64:65], off
	global_load_dwordx4 v[146:149], v[66:67], off
	v_lshl_add_u64 v[64:65], s[16:17], 0, v[170:171]
	global_load_dwordx4 v[150:153], v[64:65], off
	s_waitcnt vmcnt(16) lgkmcnt(5)
	v_mfma_f32_32x32x16_bf16 v[80:95], v[212:215], v[142:145], 0
	ds_read_b128 v[212:215], v228 offset:32864
	s_waitcnt vmcnt(15) lgkmcnt(5)
	v_mfma_f32_32x32x16_bf16 v[80:95], v[216:219], v[138:141], v[80:95]
	ds_read_b128 v[216:219], v228 offset:45664
	s_waitcnt lgkmcnt(5)
	v_mfma_f32_32x32x16_bf16 v[64:79], v[220:223], v[142:145], 0
	ds_read_b128 v[220:223], v228 offset:32896
	s_waitcnt lgkmcnt(5)
	v_mfma_f32_32x32x16_bf16 v[64:79], v[224:227], v[138:141], v[64:79]
	ds_read_b128 v[224:227], v228 offset:45696
	s_waitcnt vmcnt(14) lgkmcnt(5)
	v_mfma_f32_32x32x16_bf16 v[80:95], v[244:247], v[134:137], v[80:95]
	ds_read_b128 v[244:247], v228 offset:32928
	s_waitcnt lgkmcnt(5)
	v_mfma_f32_32x32x16_bf16 v[64:79], v[248:251], v[134:137], v[64:79]
	ds_read_b128 v[248:251], v228 offset:45728
	s_waitcnt vmcnt(13) lgkmcnt(5)
	v_mfma_f32_32x32x16_bf16 v[80:95], v[212:215], v[130:133], v[80:95]
	ds_read_b128 v[212:215], v228 offset:32960
	s_waitcnt lgkmcnt(5)
	v_mfma_f32_32x32x16_bf16 v[64:79], v[216:219], v[130:133], v[64:79]
	ds_read_b128 v[216:219], v228 offset:45760
	s_waitcnt vmcnt(12) lgkmcnt(5)
	v_mfma_f32_32x32x16_bf16 v[80:95], v[220:223], v[126:129], v[80:95]
	ds_read_b128 v[220:223], v228 offset:32992
	s_waitcnt lgkmcnt(5)
	v_mfma_f32_32x32x16_bf16 v[64:79], v[224:227], v[126:129], v[64:79]
	ds_read_b128 v[224:227], v228 offset:45792
	s_waitcnt vmcnt(11) lgkmcnt(5)
	v_mfma_f32_32x32x16_bf16 v[80:95], v[244:247], v[122:125], v[80:95]
	ds_read_b128 v[244:247], v228 offset:33024
	s_waitcnt lgkmcnt(5)
	v_mfma_f32_32x32x16_bf16 v[64:79], v[248:251], v[122:125], v[64:79]
	ds_read_b128 v[248:251], v228 offset:45824
	s_waitcnt vmcnt(10) lgkmcnt(5)
	v_mfma_f32_32x32x16_bf16 v[80:95], v[212:215], v[118:121], v[80:95]
	ds_read_b128 v[212:215], v228 offset:33056
	s_waitcnt lgkmcnt(5)
	v_mfma_f32_32x32x16_bf16 v[64:79], v[216:219], v[118:121], v[64:79]
	ds_read_b128 v[216:219], v228 offset:45856
	s_waitcnt vmcnt(9) lgkmcnt(5)
	v_mfma_f32_32x32x16_bf16 v[80:95], v[220:223], v[114:117], v[80:95]
	ds_read_b128 v[220:223], v228 offset:33088
	s_waitcnt lgkmcnt(5)
	v_mfma_f32_32x32x16_bf16 v[64:79], v[224:227], v[114:117], v[64:79]
	ds_read_b128 v[224:227], v228 offset:33120
	s_waitcnt vmcnt(8) lgkmcnt(5)
	v_mfma_f32_32x32x16_bf16 v[80:95], v[244:247], v[110:113], v[80:95]
	ds_read_b128 v[244:247], v228 offset:45888
	s_waitcnt lgkmcnt(5)
	v_mfma_f32_32x32x16_bf16 v[64:79], v[248:251], v[110:113], v[64:79]
	ds_read_b128 v[248:251], v228 offset:45920
	s_waitcnt vmcnt(7) lgkmcnt(5)
	v_mfma_f32_32x32x16_bf16 v[80:95], v[212:215], v[106:109], v[80:95]
	s_waitcnt lgkmcnt(4)
	v_mfma_f32_32x32x16_bf16 v[64:79], v[216:219], v[106:109], v[64:79]
	s_waitcnt vmcnt(6) lgkmcnt(3)
	v_mfma_f32_32x32x16_bf16 v[80:95], v[220:223], v[102:105], v[80:95]
	s_waitcnt vmcnt(5) lgkmcnt(2)
	v_mfma_f32_32x32x16_bf16 v[80:95], v[224:227], v[98:101], v[80:95]
	s_waitcnt lgkmcnt(1)
	v_mfma_f32_32x32x16_bf16 v[64:79], v[244:247], v[102:105], v[64:79]
	s_waitcnt lgkmcnt(0)
	v_mfma_f32_32x32x16_bf16 v[64:79], v[248:251], v[98:101], v[64:79]
	s_nop 7
	v_max_f32_e32 v177, v81, v81
	v_max_f32_e32 v220, v80, v80
	v_max_f32_e32 v177, v220, v177
	v_max3_f32 v177, v177, v82, v83
	v_max3_f32 v177, v177, v84, v85
	v_max3_f32 v177, v177, v86, v87
	v_max3_f32 v177, v177, v88, v89
	v_max3_f32 v177, v177, v90, v91
	v_max3_f32 v177, v177, v92, v93
	v_max3_f32 v177, v177, v94, v95
	v_max_f32_e32 v213, v204, v204
	v_max3_f32 v177, v177, v64, v65
	v_max3_f32 v177, v177, v66, v67
	v_max3_f32 v177, v177, v68, v69
	v_max3_f32 v177, v177, v70, v71
	v_max3_f32 v177, v177, v72, v73
	v_max3_f32 v177, v177, v74, v75
	v_max3_f32 v177, v177, v76, v77
	v_max3_f32 v177, v177, v78, v79
	v_mov_b32_e32 v212, v177
	s_nop 1
	v_permlane32_swap_b32_e32 v177, v212
	v_max_f32_e32 v212, v212, v212
	v_max_f32_e32 v177, v177, v177
	v_max_f32_e32 v177, v177, v212
	v_sub_f32_e32 v212, v177, v204
	v_max_f32_e32 v177, v213, v177
	v_sub_f32_e32 v213, v204, v177
	v_mul_f32_e32 v213, 0x3dd53b94, v213
	v_exp_f32_e32 v213, v213
	v_cmp_ge_f32_e32 vcc, s4, v212
	s_cmp_eq_u64 vcc, exec
	s_cselect_b64 s[10:11], -1, 0
	v_cndmask_b32_e64 v212, v213, 1.0, s[10:11]
	v_cmp_gt_f32_e32 vcc, 1.0, v212
	s_cbranch_vccz .LBB0_832
	s_and_saveexec_b64 s[12:13], s[8:9]
	ds_write_b32 v202, v212 offset:128
	s_or_b64 exec, exec, s[12:13]
	s_waitcnt lgkmcnt(0)
	v_add_u32_e32 v213, v167, v96
	ds_read_b128 v[214:217], v213 offset:224
	ds_read_b128 v[218:221], v213 offset:192
	ds_read_b128 v[222:225], v213 offset:160
	ds_read_b128 v[226:229], v213 offset:128
	s_waitcnt lgkmcnt(3)
	v_pk_mul_f32 v[60:61], v[60:61], v[214:215]
	s_waitcnt lgkmcnt(2)
	v_pk_mul_f32 v[56:57], v[56:57], v[218:219]
	s_waitcnt lgkmcnt(1)
	v_pk_mul_f32 v[52:53], v[52:53], v[222:223]
	v_pk_mul_f32 v[62:63], v[62:63], v[216:217]
	v_pk_mul_f32 v[58:59], v[58:59], v[220:221]
	v_pk_mul_f32 v[54:55], v[54:55], v[224:225]
	s_waitcnt lgkmcnt(0)
	v_pk_mul_f32 v[50:51], v[50:51], v[228:229]
	v_pk_mul_f32 v[48:49], v[48:49], v[226:227]
	v_pk_mul_f32 v[44:45], v[44:45], v[214:215]
	v_pk_mul_f32 v[40:41], v[40:41], v[218:219]
	v_pk_mul_f32 v[36:37], v[36:37], v[222:223]
	v_pk_mul_f32 v[46:47], v[46:47], v[216:217]
	v_pk_mul_f32 v[42:43], v[42:43], v[220:221]
	v_pk_mul_f32 v[38:39], v[38:39], v[224:225]
	v_pk_mul_f32 v[34:35], v[34:35], v[228:229]
	v_pk_mul_f32 v[32:33], v[32:33], v[226:227]
	v_pk_mul_f32 v[28:29], v[28:29], v[214:215]
	v_pk_mul_f32 v[24:25], v[24:25], v[218:219]
	v_pk_mul_f32 v[20:21], v[20:21], v[222:223]
	v_pk_mul_f32 v[30:31], v[30:31], v[216:217]
	v_pk_mul_f32 v[26:27], v[26:27], v[220:221]
	v_pk_mul_f32 v[22:23], v[22:23], v[224:225]
	v_pk_mul_f32 v[18:19], v[18:19], v[228:229]
	v_pk_mul_f32 v[16:17], v[16:17], v[226:227]
	v_pk_mul_f32 v[12:13], v[12:13], v[214:215]
	v_pk_mul_f32 v[8:9], v[8:9], v[218:219]
	v_pk_mul_f32 v[4:5], v[4:5], v[222:223]
	v_pk_mul_f32 v[14:15], v[14:15], v[216:217]
	v_pk_mul_f32 v[10:11], v[10:11], v[220:221]
	v_pk_mul_f32 v[6:7], v[6:7], v[224:225]
	v_pk_mul_f32 v[2:3], v[2:3], v[228:229]
	v_pk_mul_f32 v[0:1], v[0:1], v[226:227]

; __global__ void __launch_bounds__(NTHR) mega(Params p) {
	.amdhsa_kernel _Z4mega6Params
		.amdhsa_group_segment_fixed_size 16
		.amdhsa_private_segment_fixed_size 0
		.amdhsa_kernarg_size 816
		.amdhsa_user_sgpr_count 2
		.amdhsa_user_sgpr_dispatch_ptr 0
		.amdhsa_user_sgpr_queue_ptr 0
		.amdhsa_user_sgpr_kernarg_segment_ptr 1
		.amdhsa_user_sgpr_dispatch_id 0
		.amdhsa_user_sgpr_kernarg_preload_length 0
		.amdhsa_user_sgpr_kernarg_preload_offset 0
		.amdhsa_user_sgpr_private_segment_size 0
		.amdhsa_uses_dynamic_stack 0
		.amdhsa_enable_private_segment 0
		.amdhsa_system_sgpr_workgroup_id_x 1
		.amdhsa_system_sgpr_workgroup_id_y 0
		.amdhsa_system_sgpr_workgroup_id_z 0
		.amdhsa_system_sgpr_workgroup_info 0
		.amdhsa_system_vgpr_workitem_id 2
		.amdhsa_next_free_vgpr 252
		.amdhsa_next_free_sgpr 98
		.amdhsa_accum_offset 252
		.amdhsa_reserve_vcc 1
		.amdhsa_float_round_mode_32 0
		.amdhsa_float_round_mode_16_64 0
		.amdhsa_float_denorm_mode_32 3
		.amdhsa_float_denorm_mode_16_64 3
		.amdhsa_dx10_clamp 1
		.amdhsa_ieee_mode 1
		.amdhsa_fp16_overflow 0
		.amdhsa_tg_split 0
		.amdhsa_exception_fp_ieee_invalid_op 0
		.amdhsa_exception_fp_denorm_src 0
		.amdhsa_exception_fp_ieee_div_zero 0
		.amdhsa_exception_fp_ieee_overflow 0
		.amdhsa_exception_fp_ieee_underflow 0
		.amdhsa_exception_fp_ieee_inexact 0
		.amdhsa_exception_int_div_zero 0
	.end_amdhsa_kernel

; __global__ void __launch_bounds__(NTHR) mega(Params p) {
amdhsa.kernels:
  - .agpr_count:     0
    .args:
      - .offset:         0
        .size:           560
        .value_kind:     by_value
      - .offset:         560
        .size:           4
        .value_kind:     hidden_block_count_x
      - .offset:         564
        .size:           4
        .value_kind:     hidden_block_count_y
      - .offset:         568
        .size:           4
        .value_kind:     hidden_block_count_z
      - .offset:         572
        .size:           2
        .value_kind:     hidden_group_size_x
      - .offset:         574
        .size:           2
        .value_kind:     hidden_group_size_y
      - .offset:         576
        .size:           2
        .value_kind:     hidden_group_size_z
      - .offset:         578
        .size:           2
        .value_kind:     hidden_remainder_x
      - .offset:         580
        .size:           2
        .value_kind:     hidden_remainder_y
      - .offset:         582
        .size:           2
        .value_kind:     hidden_remainder_z
      - .offset:         600
        .size:           8
        .value_kind:     hidden_global_offset_x
      - .offset:         608
        .size:           8
        .value_kind:     hidden_global_offset_y
      - .offset:         616
        .size:           8
        .value_kind:     hidden_global_offset_z
      - .offset:         624
        .size:           2
        .value_kind:     hidden_grid_dims
      - .offset:         648
        .size:           8
        .value_kind:     hidden_multigrid_sync_arg
      - .offset:         680
        .size:           4
        .value_kind:     hidden_dynamic_lds_size
    .group_segment_fixed_size: 16
    .kernarg_segment_align: 8
    .kernarg_segment_size: 816
    .language:       OpenCL C
    .language_version:
      - 2
      - 0
    .max_flat_workgroup_size: 512
    .name:           _Z4mega6Params
    .private_segment_fixed_size: 0
    .sgpr_count:     104
    .sgpr_spill_count: 59
    .symbol:         _Z4mega6Params.kd
    .uniform_work_group_size: 1
    .uses_dynamic_stack: false
    .vgpr_count:     252
    .vgpr_spill_count: 0
    .wavefront_size: 64
